# k44: k42 + waitcnt placement in the attention tile loop (iteration-top wait covers only the logf row, K/V register wait moved down to their ds_write)
# baseline (speedup 1.0000x reference)
; #define LAS __attribute__((address_space(3)))
; template <bool BAND>
; __device__ __forceinline__ void tile_body(f32x16* o, float& l_reg, const bf16x8* qr, const LAS unsigned char* kbs, const LAS float* wb, int vb, float ci, int hi, int keybase, int qabs) {
;     f32x16 p0, p1;
; #pragma unroll
;     for (int g4 = 0; g4 < 4; ++g4) {
;         const f32x4 ba = *(const LAS f32x4*)(wb + 8 * g4 + 4 * hi) + ci, bb = *(const LAS f32x4*)(wb + 32 + 8 * g4 + 4 * hi) + ci;
; #pragma unroll
;         for (int e = 0; e < 4; ++e) { p0[4 * g4 + e] = ba[e]; p1[4 * g4 + e] = bb[e]; }
;     }
; #pragma unroll
;     for (int d0 = 0; d0 < 4; ++d0) {
;         const bf16x8 b0 = *(const LAS bf16x8*)(kbs + d0 * 2048), b1 = *(const LAS bf16x8*)(kbs + d0 * 2048 + 512);
;         p0 = __builtin_amdgcn_mfma_f32_32x32x16_bf16(b0, qr[d0], p0, 0, 0, 0); p1 = __builtin_amdgcn_mfma_f32_32x32x16_bf16(b1, qr[d0], p1, 0, 0, 0); }
.LBB0_777:
	s_waitcnt lgkmcnt(0)
	s_barrier
	s_waitcnt vmcnt(8)
	s_nop 1
	v_add_f32_dpp v0, v140, v140 row_shl:1 row_mask:0xf bank_mask:0xf bound_ctrl:1
	s_nop 1
	v_add_f32_dpp v0, v0, v0 row_shl:2 row_mask:0xf bank_mask:0xf bound_ctrl:1
	s_nop 1
	v_add_f32_dpp v0, v0, v0 row_shl:4 row_mask:0xf bank_mask:0xf bound_ctrl:1
	s_nop 1
	v_add_f32_dpp v0, v0, v0 row_shl:8 row_mask:0xf bank_mask:0xf bound_ctrl:1
	s_nop 0
	v_readlane_b32 s28, v0, 16
	v_readlane_b32 s67, v0, 32
	v_readlane_b32 s66, v0, 48
	s_and_saveexec_b64 s[12:13], s[6:7]
	s_xor_b64 s[12:13], exec, s[12:13]
	s_cbranch_execz .LBB0_783
	s_and_saveexec_b64 s[64:65], s[8:9]
	s_xor_b64 s[64:65], exec, s[64:65]
	v_mov_b32_e32 v149, s66
	v_cndmask_b32_e64 v149, 0, v149, s[10:11]
	s_andn2_saveexec_b64 s[64:65], s[64:65]
	v_mov_b32_e32 v149, s66
	v_add_f32_e32 v149, s67, v149
	s_or_b64 exec, exec, s[64:65]
.LBB0_783:
	s_andn2_saveexec_b64 s[12:13], s[12:13]
	v_mov_b32_e32 v149, s67
	v_add_f32_e32 v149, s28, v149
	v_add_f32_e32 v149, s66, v149
	s_or_b64 exec, exec, s[12:13]
	v_add_f32_e32 v149, v0, v149
	s_xor_b32 s74, s70, 1
	v_add_f32_e32 v0, v150, v149
	s_lshl_b32 s12, s74, 8
	v_sub_f32_e32 v0, v0, v140
	s_add_i32 s71, s53, s12
	s_lshl_b32 s78, s74, 14
	s_max_i32 s12, s48, 4
	v_mul_f32_e32 v140, 0x3fb8aa3b, v0
	v_lshl_add_u32 v0, v137, 2, s71
	v_readfirstlane_b32 s76, v149
	v_add_u32_e32 v149, s78, v143
	s_add_i32 s28, s12, -4
	ds_write_b32 v0, v140 offset:32768
	s_waitcnt vmcnt(4)
	ds_write_b128 v149, v[66:69]
	ds_write_b128 v149, v[74:77] offset:8192
	s_lshl_b64 s[12:13], s[28:29], 11
	s_waitcnt lgkmcnt(0)
	v_lshl_add_u64 v[66:67], v[110:111], 0, s[12:13]
	s_lshl_b64 s[12:13], s[28:29], 16
	global_load_dword v140, v[66:67], off
	v_lshl_add_u64 v[74:75], v[106:107], 0, s[12:13]
	global_load_dwordx4 v[66:69], v[74:75], off
	v_cndmask_b32_e64 v74, 0, 1, s[58:59]
	v_lshl_add_u64 v[152:153], v[108:109], 0, s[12:13]
	v_cmp_ne_u32_e64 s[12:13], 1, v74
	global_load_dwordx4 v[74:77], v[152:153], off
	s_andn2_b64 vcc, exec, s[58:59]
	s_cbranch_vccnz .LBB0_792
	s_and_b64 vcc, exec, s[98:99]
	s_cbranch_vccnz .LBB0_792
	s_sub_i32 s28, s75, 64
	s_cmp_gt_i32 s28, s73
	s_cbranch_scc1 .LBB0_792
	s_lshl_b32 s64, s70, 8
	s_lshl_b32 s28, s70, 14
	s_add_i32 s66, s53, s64
	s_cmp_lt_i32 s48, s72
	v_add_u32_e32 v151, s28, v144
	s_mov_b64 s[64:65], -1
	v_add_u32_e32 v152, s28, v145
	v_lshl_add_u32 v153, v142, 2, s66
	s_cbranch_scc1 .LBB0_789
	ds_read_b128 v[34:37], v153 offset:32768
	ds_read_b128 v[38:41], v153 offset:32800
	ds_read_b128 v[42:45], v153 offset:32832
	ds_read_b128 v[46:49], v153 offset:32864
	ds_read_b128 v[50:53], v153 offset:32896
	ds_read_b128 v[54:57], v153 offset:32928
	ds_read_b128 v[58:61], v153 offset:32960
	ds_read_b128 v[62:65], v153 offset:32992
	ds_read_b128 v[154:157], v152
	ds_read_b128 v[158:161], v152 offset:512
	s_waitcnt lgkmcnt(4)
	ds_read_b128 v[210:213], v152 offset:2048
	ds_read_b128 v[214:217], v152 offset:2560
	ds_read_b128 v[218:221], v152 offset:4096
	ds_read_b128 v[222:225], v152 offset:4608
	ds_read_b128 v[226:229], v152 offset:6656
	ds_read_b128 v[230:233], v152 offset:6144
	v_pk_add_f32 v[56:57], v[118:119], v[56:57]
	s_waitcnt lgkmcnt(9)
	v_pk_add_f32 v[60:61], v[122:123], v[60:61]
	s_waitcnt lgkmcnt(8)
	v_pk_add_f32 v[64:65], v[126:127], v[64:65]
	v_pk_add_f32 v[52:53], v[114:115], v[52:53]
	v_pk_add_f32 v[62:63], v[124:125], v[62:63]
	v_pk_add_f32 v[58:59], v[120:121], v[58:59]
	v_pk_add_f32 v[54:55], v[116:117], v[54:55]
	v_pk_add_f32 v[50:51], v[112:113], v[50:51]
	v_pk_add_f32 v[48:49], v[126:127], v[48:49]
	v_pk_add_f32 v[44:45], v[122:123], v[44:45]
	v_pk_add_f32 v[40:41], v[118:119], v[40:41]
	v_pk_add_f32 v[36:37], v[114:115], v[36:37]
	v_pk_add_f32 v[46:47], v[124:125], v[46:47]
	v_pk_add_f32 v[42:43], v[120:121], v[42:43]
	v_pk_add_f32 v[38:39], v[116:117], v[38:39]
	v_pk_add_f32 v[34:35], v[112:113], v[34:35]
	s_waitcnt lgkmcnt(6)
	v_mfma_f32_32x32x16_bf16 v[50:65], v[158:161], v[94:97], v[50:65]
	v_mfma_f32_32x32x16_bf16 v[34:49], v[154:157], v[94:97], v[34:49]
	s_waitcnt lgkmcnt(4)
	v_mfma_f32_32x32x16_bf16 v[50:65], v[214:217], v[98:101], v[50:65]
	v_mfma_f32_32x32x16_bf16 v[34:49], v[210:213], v[98:101], v[34:49]
	s_waitcnt lgkmcnt(2)
	v_mfma_f32_32x32x16_bf16 v[50:65], v[222:225], v[102:105], v[50:65]
	v_mfma_f32_32x32x16_bf16 v[34:49], v[218:221], v[102:105], v[34:49]
	s_waitcnt lgkmcnt(1)
	v_mfma_f32_32x32x16_bf16 v[50:65], v[226:229], v[90:93], v[50:65]
	v_add_u32_e32 v154, s75, v142
	v_subrev_u32_e32 v156, 32, v154
	v_subrev_u32_e32 v155, 64, v154
	v_cmp_le_i32_e32 vcc, v156, v147
	s_waitcnt lgkmcnt(0)
; __device__ __forceinline__ void pv(f32x16* o, int vb, bf16x8 pa0, bf16x8 pa1, bf16x8 pa2, bf16x8 pa3) {
; #pragma unroll
;     for (int d0 = 0; d0 < 2; ++d0) { s16x4 lo[4], hi[4];
; #pragma unroll
;         for (int ks = 0; ks < 4; ++ks) {
;             asm volatile("ds_read_b64_tr_b16 %0,%1 offset:%c2" : "=&v"(lo[ks]) : "v"(vb), "i"(d0 * 4096 + ks * 1024) : "memory");
;             asm volatile("ds_read_b64_tr_b16 %0,%1 offset:%c2" : "=&v"(hi[ks]) : "v"(vb), "i"(d0 * 4096 + ks * 1024 + 512) : "memory"); }
;         asm volatile("s_waitcnt lgkmcnt(0)" ::: "memory"); __builtin_amdgcn_sched_barrier(0);
;     ...
;         o[d0] = __builtin_amdgcn_mfma_f32_32x32x16_bf16(pa0, PK(0), o[d0], 0, 0, 0);
;         o[d0] = __builtin_amdgcn_mfma_f32_32x32x16_bf16(pa1, PK(1), o[d0], 0, 0, 0);
;         o[d0] = __builtin_amdgcn_mfma_f32_32x32x16_bf16(pa2, PK(2), o[d0], 0, 0, 0);
;         o[d0] = __builtin_amdgcn_mfma_f32_32x32x16_bf16(pa3, PK(3), o[d0], 0, 0, 0);
; template <bool BAND>
; __device__ __forceinline__ void tile_body(f32x16* o, float& l_reg, const bf16x8* qr, const LAS unsigned char* kbs, const LAS float* wb, int vb, float ci, int hi, int keybase, int qabs) {
;     ...
;     if (BAND) {
; #pragma unroll
;         for (int r = 0; r < 16; ++r) { const int key = keybase + 8 * (r >> 2) + (r & 3); if (key > qabs) p0[r] = -INFINITY; if (key + 32 > qabs) p1[r] = -INFINITY; }
;     }
;     f32x2 s2 = {0.f, 0.f};
; #pragma unroll
;     for (int r = 0; r < 16; r += 2) {
;         p0[r] = __builtin_amdgcn_exp2f(p0[r]); p0[r + 1] = __builtin_amdgcn_exp2f(p0[r + 1]); p1[r] = __builtin_amdgcn_exp2f(p1[r]); p1[r + 1] = __builtin_amdgcn_exp2f(p1[r + 1]);
;         s2 += (f32x2){p0[r], p0[r + 1]}; s2 += (f32x2){p1[r], p1[r + 1]}; }
;     l_reg += s2.x + s2.y;
;     u32x4 pw0, pw1, pw2, pw3;
;     pw0 = (u32x4){cvtpk(p0[0], p0[1]), cvtpk(p0[2], p0[3]), cvtpk(p0[4], p0[5]), cvtpk(p0[6], p0[7])};
;     pw1 = (u32x4){cvtpk(p0[8], p0[9]), cvtpk(p0[10], p0[11]), cvtpk(p0[12], p0[13]), cvtpk(p0[14], p0[15])};
;     pw2 = (u32x4){cvtpk(p1[0], p1[1]), cvtpk(p1[2], p1[3]), cvtpk(p1[4], p1[5]), cvtpk(p1[6], p1[7])};
;     pw3 = (u32x4){cvtpk(p1[8], p1[9]), cvtpk(p1[10], p1[11]), cvtpk(p1[12], p1[13]), cvtpk(p1[14], p1[15])};
;     pv(o, vb, __builtin_bit_cast(bf16x8, pw0), __builtin_bit_cast(bf16x8, pw1), __builtin_bit_cast(bf16x8, pw2), __builtin_bit_cast(bf16x8, pw3));
	v_mfma_f32_32x32x16_bf16 v[34:49], v[230:233], v[90:93], v[34:49]
	s_nop 5
	v_cndmask_b32_e32 v50, v134, v50, vcc
	v_cmp_lt_i32_e32 vcc, v155, v147
	s_nop 3
	v_cndmask_b32_e32 v35, v134, v35, vcc
	v_cmp_le_i32_e32 vcc, v155, v147
	v_subrev_u32_e32 v155, 31, v154
	v_exp_f32_e32 v35, v35
	v_cndmask_b32_e32 v34, v134, v34, vcc
	v_cmp_le_i32_e32 vcc, v155, v147
	v_subrev_u32_e32 v155, 62, v154
	v_exp_f32_e32 v34, v34
	v_cndmask_b32_e32 v51, v134, v51, vcc
	v_cmp_le_i32_e32 vcc, v155, v147
	s_nop 1
	v_cndmask_b32_e32 v155, v134, v36, vcc
	v_subrev_u32_e32 v36, 30, v154
	v_cmp_le_i32_e32 vcc, v36, v147
	v_subrev_u32_e32 v36, 61, v154
	s_nop 0
	v_cndmask_b32_e32 v52, v134, v52, vcc
	v_cmp_le_i32_e32 vcc, v36, v147
	v_subrev_u32_e32 v36, 29, v154
	s_nop 0
	v_cndmask_b32_e32 v156, v134, v37, vcc
	v_cmp_le_i32_e32 vcc, v36, v147
	v_subrev_u32_e32 v36, 56, v154
	v_exp_f32_e32 v37, v51
	v_cndmask_b32_e32 v53, v134, v53, vcc
	v_cmp_le_i32_e32 vcc, v36, v147
	v_subrev_u32_e32 v36, 24, v154
	s_nop 0
	v_cndmask_b32_e32 v157, v134, v38, vcc
	v_cmp_le_i32_e32 vcc, v36, v147
	v_subrev_u32_e32 v36, 55, v154
	v_exp_f32_e32 v38, v155
	v_cndmask_b32_e32 v54, v134, v54, vcc
	v_cmp_le_i32_e32 vcc, v36, v147
	v_subrev_u32_e32 v36, 23, v154
	s_nop 0
	v_cndmask_b32_e32 v158, v134, v39, vcc
	v_cmp_le_i32_e32 vcc, v36, v147
	v_subrev_u32_e32 v36, 54, v154
	v_exp_f32_e32 v39, v156
	v_cndmask_b32_e32 v55, v134, v55, vcc
	v_cmp_le_i32_e32 vcc, v36, v147
	v_subrev_u32_e32 v36, 22, v154
	v_cvt_pk_bf16_f32 v156, v34, v35
	v_cndmask_b32_e32 v159, v134, v40, vcc
	v_cmp_le_i32_e32 vcc, v36, v147
	v_subrev_u32_e32 v36, 53, v154
	v_exp_f32_e32 v40, v52
	v_cndmask_b32_e32 v56, v134, v56, vcc
	v_cmp_le_i32_e32 vcc, v36, v147
	v_subrev_u32_e32 v36, 21, v154
	s_nop 0
	v_cndmask_b32_e32 v160, v134, v41, vcc
	v_cmp_le_i32_e32 vcc, v36, v147
	v_subrev_u32_e32 v36, 48, v154
	v_exp_f32_e32 v41, v53
	v_cndmask_b32_e32 v57, v134, v57, vcc
	v_cmp_le_i32_e32 vcc, v36, v147
	v_add_u32_e32 v36, -16, v154
	v_exp_f32_e32 v51, v57
	v_cndmask_b32_e32 v161, v134, v42, vcc
	v_cmp_le_i32_e32 vcc, v36, v147
	v_subrev_u32_e32 v36, 47, v154
	v_exp_f32_e32 v52, v161
	v_cndmask_b32_e32 v58, v134, v58, vcc
	v_cmp_le_i32_e32 vcc, v36, v147
	v_add_u32_e32 v36, -15, v154
	s_nop 0
	v_cndmask_b32_e32 v162, v134, v43, vcc
	v_cmp_le_i32_e32 vcc, v36, v147
	v_subrev_u32_e32 v36, 46, v154
	v_pk_add_f32 v[42:43], v[34:35], 0 op_sel_hi:[1,0]
	v_cndmask_b32_e32 v59, v134, v59, vcc
	v_cmp_le_i32_e32 vcc, v36, v147
	v_add_u32_e32 v36, -14, v154
	v_exp_f32_e32 v53, v162
	v_cndmask_b32_e32 v163, v134, v44, vcc
	v_cmp_le_i32_e32 vcc, v36, v147
	v_subrev_u32_e32 v36, 45, v154
	v_exp_f32_e32 v44, v157
	v_cndmask_b32_e32 v60, v134, v60, vcc
	v_cmp_le_i32_e32 vcc, v36, v147
	v_add_u32_e32 v36, -13, v154
	v_cvt_pk_bf16_f32 v157, v38, v39
	v_cndmask_b32_e32 v164, v134, v45, vcc
	v_cmp_le_i32_e32 vcc, v36, v147
	v_subrev_u32_e32 v36, 40, v154
	v_exp_f32_e32 v45, v158
	v_cndmask_b32_e32 v61, v134, v61, vcc
	v_cmp_le_i32_e32 vcc, v36, v147
	v_add_u32_e32 v36, -8, v154
	v_exp_f32_e32 v57, v164
	v_cndmask_b32_e32 v165, v134, v46, vcc
	v_cmp_le_i32_e32 vcc, v36, v147
	v_subrev_u32_e32 v36, 39, v154
	v_exp_f32_e32 v46, v54
	v_cndmask_b32_e32 v62, v134, v62, vcc
	v_cmp_le_i32_e32 vcc, v36, v147
	v_add_u32_e32 v36, -7, v154
	v_exp_f32_e32 v54, v58
	v_cndmask_b32_e32 v166, v134, v47, vcc
	v_cmp_le_i32_e32 vcc, v36, v147
	v_subrev_u32_e32 v36, 38, v154
	v_exp_f32_e32 v47, v55
	v_cndmask_b32_e32 v63, v134, v63, vcc
	v_cmp_le_i32_e32 vcc, v36, v147
	v_add_u32_e32 v36, -6, v154
	v_exp_f32_e32 v55, v59
	v_cndmask_b32_e32 v167, v134, v48, vcc
	v_cmp_le_i32_e32 vcc, v36, v147
	v_subrev_u32_e32 v36, 37, v154
	v_exp_f32_e32 v48, v159
	v_cndmask_b32_e32 v168, v134, v64, vcc
	v_cmp_le_i32_e32 vcc, v36, v147
	v_add_u32_e32 v36, -5, v154
	v_exp_f32_e32 v58, v60
	v_cndmask_b32_e32 v169, v134, v49, vcc
	v_cmp_le_i32_e32 vcc, v36, v147
	v_exp_f32_e32 v36, v50
	v_exp_f32_e32 v49, v160
	v_exp_f32_e32 v50, v56
	v_exp_f32_e32 v56, v163
	v_pk_add_f32 v[42:43], v[36:37], v[42:43]
	v_exp_f32_e32 v59, v61
	v_pk_add_f32 v[42:43], v[38:39], v[42:43]
	v_exp_f32_e32 v64, v167
	v_pk_add_f32 v[42:43], v[40:41], v[42:43]
	v_cvt_pk_bf16_f32 v167, v50, v51
	v_pk_add_f32 v[42:43], v[44:45], v[42:43]
	v_exp_f32_e32 v60, v165
	v_pk_add_f32 v[42:43], v[46:47], v[42:43]
	v_exp_f32_e32 v61, v166
	v_pk_add_f32 v[42:43], v[48:49], v[42:43]
	v_cvt_pk_bf16_f32 v160, v52, v53
	v_pk_add_f32 v[42:43], v[50:51], v[42:43]
	ds_read_b64_tr_b16 v[50:51],v151 offset:0
	v_exp_f32_e32 v62, v62
	v_pk_add_f32 v[42:43], v[52:53], v[42:43]
	ds_read_b64_tr_b16 v[52:53],v151 offset:512
	v_exp_f32_e32 v63, v63
	v_pk_add_f32 v[42:43], v[54:55], v[42:43]
	v_exp_f32_e32 v172, v168
	v_cvt_pk_bf16_f32 v168, v54, v55
	ds_read_b64_tr_b16 v[54:55],v151 offset:1024
	v_cndmask_b32_e32 v154, v134, v65, vcc
	v_pk_add_f32 v[42:43], v[56:57], v[42:43]
	v_exp_f32_e32 v65, v169
	v_cvt_pk_bf16_f32 v161, v56, v57
	ds_read_b64_tr_b16 v[56:57],v151 offset:1536
	v_pk_add_f32 v[42:43], v[58:59], v[42:43]
	v_exp_f32_e32 v173, v154
	v_cvt_pk_bf16_f32 v169, v58, v59
	ds_read_b64_tr_b16 v[58:59],v151 offset:2048
	v_pk_add_f32 v[42:43], v[60:61], v[42:43]
	v_cvt_pk_bf16_f32 v162, v60, v61
	ds_read_b64_tr_b16 v[60:61],v151 offset:2560
	v_pk_add_f32 v[42:43], v[62:63], v[42:43]
	v_cvt_pk_bf16_f32 v170, v62, v63
	ds_read_b64_tr_b16 v[62:63],v151 offset:3072
	v_pk_add_f32 v[42:43], v[64:65], v[42:43]
	v_cvt_pk_bf16_f32 v163, v64, v65
	ds_read_b64_tr_b16 v[64:65],v151 offset:3584
	v_pk_add_f32 v[42:43], v[172:173], v[42:43]
	s_waitcnt lgkmcnt(0)
	v_cvt_pk_bf16_f32 v158, v44, v45
	v_add_f32_e32 v42, v42, v43
	v_add_f32_e32 v154, v148, v42
	v_cvt_pk_bf16_f32 v159, v48, v49
	v_cvt_pk_bf16_f32 v164, v36, v37
	v_cvt_pk_bf16_f32 v165, v40, v41
	v_cvt_pk_bf16_f32 v166, v46, v47
	v_cvt_pk_bf16_f32 v171, v172, v173
	v_mfma_f32_32x32x16_bf16 v[2:17], v[156:159], v[50:53], v[2:17]
	ds_read_b64_tr_b16 v[172:173],v151 offset:4096
	ds_read_b64_tr_b16 v[174:175],v151 offset:4608
	ds_read_b64_tr_b16 v[176:177],v151 offset:5120
	ds_read_b64_tr_b16 v[178:179],v151 offset:5632
	ds_read_b64_tr_b16 v[180:181],v151 offset:6144
	ds_read_b64_tr_b16 v[182:183],v151 offset:6656
	ds_read_b64_tr_b16 v[184:185],v151 offset:7168
	v_mfma_f32_32x32x16_bf16 v[2:17], v[160:163], v[54:57], v[2:17]
	ds_read_b64_tr_b16 v[186:187],v151 offset:7680
	s_waitcnt lgkmcnt(0)
	v_mfma_f32_32x32x16_bf16 v[2:17], v[164:167], v[58:61], v[2:17]
	v_mfma_f32_32x32x16_bf16 v[2:17], v[168:171], v[62:65], v[2:17]
	v_mfma_f32_32x32x16_bf16 v[18:33], v[156:159], v[172:175], v[18:33]
	s_mov_b64 s[64:65], 0
	v_mfma_f32_32x32x16_bf16 v[18:33], v[160:163], v[176:179], v[18:33]
	v_mfma_f32_32x32x16_bf16 v[18:33], v[164:167], v[180:183], v[18:33]
	v_mfma_f32_32x32x16_bf16 v[18:33], v[168:171], v[184:187], v[18:33]

.LBB0_792:
	s_cmp_lg_u32 s48, 0
	v_fma_f32 v151, v150, s50, -v146
	s_cselect_b64 s[64:65], -1, 0
	v_cmp_nlt_f32_e64 s[66:67], v151, -v131
	v_fma_f32 v196, v150, s50, -v197
	v_cmp_lt_f32_e64 s[100:101], v196, -v131
	s_nop 3
	s_or_b64 s[98:99], s[98:99], s[100:101]
	s_and_b64 s[68:69], s[64:65], s[66:67]
	s_mov_b64 s[66:67], -1
	s_and_saveexec_b64 s[64:65], s[68:69]
	s_cbranch_execz .LBB0_776
	s_waitcnt lgkmcnt(0)
	s_barrier
	s_waitcnt vmcnt(8)
	s_nop 1
	v_add_f32_dpp v151, v141, v141 row_shl:1 row_mask:0xf bank_mask:0xf bound_ctrl:1
	s_nop 1
	v_add_f32_dpp v151, v151, v151 row_shl:2 row_mask:0xf bank_mask:0xf bound_ctrl:1
	s_nop 1
	v_add_f32_dpp v151, v151, v151 row_shl:4 row_mask:0xf bank_mask:0xf bound_ctrl:1
	s_nop 1
	v_add_f32_dpp v152, v151, v151 row_shl:8 row_mask:0xf bank_mask:0xf bound_ctrl:1
	s_nop 0
	v_readlane_b32 s28, v152, 16
	v_readlane_b32 s79, v152, 32
	v_readlane_b32 s77, v152, 48
	s_and_saveexec_b64 s[66:67], s[6:7]
	s_xor_b64 s[66:67], exec, s[66:67]
	s_cbranch_execz .LBB0_799
	s_and_saveexec_b64 s[68:69], s[8:9]
	s_xor_b64 s[68:69], exec, s[68:69]
	v_mov_b32_e32 v151, s77
	v_cndmask_b32_e64 v153, 0, v151, s[10:11]
	s_andn2_saveexec_b64 s[68:69], s[68:69]
	v_mov_b32_e32 v151, s77
	v_add_f32_e32 v153, s79, v151
	s_or_b64 exec, exec, s[68:69]
.LBB0_799:
	s_andn2_saveexec_b64 s[66:67], s[66:67]
	v_mov_b32_e32 v151, s79
	v_add_f32_e32 v151, s28, v151
	v_add_f32_e32 v153, s77, v151
	s_or_b64 exec, exec, s[66:67]
	v_add_f32_e32 v151, s76, v150
	v_add_f32_e32 v150, v152, v153
	v_add_f32_e32 v152, v151, v150
	s_lshl_b32 s28, s70, 8
	v_sub_f32_e32 v141, v152, v141
	s_add_i32 s76, s53, s28
	v_mul_f32_e32 v141, 0x3fb8aa3b, v141
	v_lshl_add_u32 v152, v137, 2, s76
	s_lshl_b32 s77, s70, 14
	ds_write_b32 v152, v141 offset:32768
	v_add_u32_e32 v141, s77, v143
	s_max_i32 s28, s48, 5
	s_waitcnt vmcnt(4)
	ds_write_b128 v141, v[70:73]
	ds_write_b128 v141, v[82:85] offset:8192
	s_add_i32 s28, s28, -5
	s_waitcnt lgkmcnt(0)
	s_lshl_b64 s[66:67], s[28:29], 11
	v_lshl_add_u64 v[70:71], v[110:111], 0, s[66:67]
	global_load_dword v141, v[70:71], off
	s_lshl_b64 s[66:67], s[28:29], 16
	v_lshl_add_u64 v[82:83], v[106:107], 0, s[66:67]
	global_load_dwordx4 v[70:73], v[82:83], off
	v_lshl_add_u64 v[152:153], v[108:109], 0, s[66:67]
	global_load_dwordx4 v[82:85], v[152:153], off
	v_readfirstlane_b32 s79, v150
	s_and_b64 vcc, exec, s[12:13]
	s_cbranch_vccnz .LBB0_808
	s_and_b64 vcc, exec, s[98:99]
	s_cbranch_vccnz .LBB0_808
	s_add_i32 s28, s75, 0xffffff80
	s_cmp_gt_i32 s28, s73
	s_cbranch_scc1 .LBB0_808
	s_cmp_le_i32 s48, s72
	v_add_u32_e32 v150, s78, v144
	s_mov_b64 s[66:67], -1
	v_add_u32_e32 v152, s78, v145
	v_lshl_add_u32 v153, v142, 2, s71
	s_cbranch_scc0 .LBB0_805
; #define LAS __attribute__((address_space(3)))
; __device__ __forceinline__ unsigned cvtpk(float lo, float hi) { typedef __bf16 bf16x2_t __attribute__((ext_vector_type(2))); f32x2 v = {lo, hi}; bf16x2_t b = __builtin_convertvector(v, bf16x2_t); return __builtin_bit_cast(unsigned, b); }
; template <bool BAND>
; __device__ __forceinline__ void tile_body(f32x16* o, float& l_reg, const bf16x8* qr, const LAS unsigned char* kbs, const LAS float* wb, int vb, float ci, int hi, int keybase, int qabs) {
;     f32x16 p0, p1;
; #pragma unroll
;     for (int g4 = 0; g4 < 4; ++g4) {
;         const f32x4 ba = *(const LAS f32x4*)(wb + 8 * g4 + 4 * hi) + ci, bb = *(const LAS f32x4*)(wb + 32 + 8 * g4 + 4 * hi) + ci;
; #pragma unroll
;         for (int e = 0; e < 4; ++e) { p0[4 * g4 + e] = ba[e]; p1[4 * g4 + e] = bb[e]; }
;     }
; #pragma unroll
;     for (int d0 = 0; d0 < 4; ++d0) {
;         const bf16x8 b0 = *(const LAS bf16x8*)(kbs + d0 * 2048), b1 = *(const LAS bf16x8*)(kbs + d0 * 2048 + 512);
;         p0 = __builtin_amdgcn_mfma_f32_32x32x16_bf16(b0, qr[d0], p0, 0, 0, 0); p1 = __builtin_amdgcn_mfma_f32_32x32x16_bf16(b1, qr[d0], p1, 0, 0, 0); }
;     if (BAND) {
; #pragma unroll
;         for (int r = 0; r < 16; ++r) { const int key = keybase + 8 * (r >> 2) + (r & 3); if (key > qabs) p0[r] = -INFINITY; if (key + 32 > qabs) p1[r] = -INFINITY; }
;     }
;     f32x2 s2 = {0.f, 0.f};
; #pragma unroll
;     for (int r = 0; r < 16; r += 2) {
;         p0[r] = __builtin_amdgcn_exp2f(p0[r]); p0[r + 1] = __builtin_amdgcn_exp2f(p0[r + 1]); p1[r] = __builtin_amdgcn_exp2f(p1[r]); p1[r + 1] = __builtin_amdgcn_exp2f(p1[r + 1]);
;         s2 += (f32x2){p0[r], p0[r + 1]}; s2 += (f32x2){p1[r], p1[r + 1]}; }
;     l_reg += s2.x + s2.y;
;     u32x4 pw0, pw1, pw2, pw3;
;     pw0 = (u32x4){cvtpk(p0[0], p0[1]), cvtpk(p0[2], p0[3]), cvtpk(p0[4], p0[5]), cvtpk(p0[6], p0[7])};
;     pw1 = (u32x4){cvtpk(p0[8], p0[9]), cvtpk(p0[10], p0[11]), cvtpk(p0[12], p0[13]), cvtpk(p0[14], p0[15])};
;     pw2 = (u32x4){cvtpk(p1[0], p1[1]), cvtpk(p1[2], p1[3]), cvtpk(p1[4], p1[5]), cvtpk(p1[6], p1[7])};
;     pw3 = (u32x4){cvtpk(p1[8], p1[9]), cvtpk(p1[10], p1[11]), cvtpk(p1[12], p1[13]), cvtpk(p1[14], p1[15])};
;     pv(o, vb, __builtin_bit_cast(bf16x8, pw0), __builtin_bit_cast(bf16x8, pw1), __builtin_bit_cast(bf16x8, pw2), __builtin_bit_cast(bf16x8, pw3));
	ds_read_b128 v[34:37], v153 offset:32768
	ds_read_b128 v[38:41], v153 offset:32800
	ds_read_b128 v[42:45], v153 offset:32832
	ds_read_b128 v[46:49], v153 offset:32864
	ds_read_b128 v[50:53], v153 offset:32896
	ds_read_b128 v[54:57], v153 offset:32928
	ds_read_b128 v[58:61], v153 offset:32960
	ds_read_b128 v[62:65], v153 offset:32992
	ds_read_b128 v[154:157], v152
	ds_read_b128 v[158:161], v152 offset:512
	s_waitcnt lgkmcnt(6)
	ds_read_b128 v[210:213], v152 offset:2048
	ds_read_b128 v[214:217], v152 offset:2560
	ds_read_b128 v[218:221], v152 offset:4096
	ds_read_b128 v[222:225], v152 offset:4608
	ds_read_b128 v[226:229], v152 offset:6144
	ds_read_b128 v[230:233], v152 offset:6656
	v_pk_add_f32 v[48:49], v[126:127], v[48:49]
	v_pk_add_f32 v[44:45], v[122:123], v[44:45]
	v_pk_add_f32 v[40:41], v[118:119], v[40:41]
	v_pk_add_f32 v[36:37], v[114:115], v[36:37]
	v_pk_add_f32 v[46:47], v[124:125], v[46:47]
	v_pk_add_f32 v[42:43], v[120:121], v[42:43]
	v_pk_add_f32 v[38:39], v[116:117], v[38:39]
	v_pk_add_f32 v[34:35], v[112:113], v[34:35]
	s_waitcnt lgkmcnt(8)
	v_pk_add_f32 v[64:65], v[126:127], v[64:65]
	v_pk_add_f32 v[60:61], v[122:123], v[60:61]
	s_waitcnt lgkmcnt(7)
	v_mfma_f32_32x32x16_bf16 v[34:49], v[154:157], v[94:97], v[34:49]
	v_add_f32_e64 v56, v118, v56
	v_add_f32_e64 v57, v119, v57
	v_add_f32_e64 v52, v114, v52
	v_add_f32_e64 v53, v115, v53
	v_add_f32_e64 v62, v124, v62
	v_add_f32_e64 v63, v125, v63
	v_pk_add_f32 v[58:59], v[120:121], v[58:59]
	v_pk_add_f32 v[54:55], v[116:117], v[54:55]
	v_pk_add_f32 v[50:51], v[112:113], v[50:51]
	s_waitcnt lgkmcnt(6)
	s_nop 0
	v_mfma_f32_32x32x16_bf16 v[50:65], v[158:161], v[94:97], v[50:65]
	s_waitcnt lgkmcnt(5)
	v_mfma_f32_32x32x16_bf16 v[34:49], v[210:213], v[98:101], v[34:49]
	s_waitcnt lgkmcnt(4)
	v_mfma_f32_32x32x16_bf16 v[50:65], v[214:217], v[98:101], v[50:65]
	s_waitcnt lgkmcnt(3)
	v_mfma_f32_32x32x16_bf16 v[34:49], v[218:221], v[102:105], v[34:49]
	s_waitcnt lgkmcnt(2)
	v_mfma_f32_32x32x16_bf16 v[50:65], v[222:225], v[102:105], v[50:65]
	s_waitcnt lgkmcnt(1)
	v_mfma_f32_32x32x16_bf16 v[34:49], v[226:229], v[90:93], v[34:49]
	s_waitcnt lgkmcnt(0)
	v_mfma_f32_32x32x16_bf16 v[50:65], v[230:233], v[90:93], v[50:65]
	s_nop 9
	v_exp_f32_e32 v34, v34
	v_exp_f32_e32 v35, v35
	v_exp_f32_e32 v36, v36
	v_exp_f32_e32 v37, v37
	v_exp_f32_e32 v38, v38
	v_pk_add_f32 v[154:155], v[34:35], 0 op_sel_hi:[1,0]
	v_exp_f32_e32 v39, v39
	v_exp_f32_e32 v50, v50
	v_exp_f32_e32 v51, v51
	v_exp_f32_e32 v52, v52
	v_exp_f32_e32 v53, v53
	v_exp_f32_e32 v54, v54
	v_pk_add_f32 v[154:155], v[50:51], v[154:155]
	v_exp_f32_e32 v55, v55
	v_pk_add_f32 v[154:155], v[36:37], v[154:155]
	v_exp_f32_e32 v40, v40
	v_exp_f32_e32 v41, v41
	v_pk_add_f32 v[154:155], v[52:53], v[154:155]
	v_exp_f32_e32 v56, v56
	v_exp_f32_e32 v57, v57
	v_pk_add_f32 v[154:155], v[38:39], v[154:155]
	v_exp_f32_e32 v42, v42
	v_exp_f32_e32 v43, v43
	v_pk_add_f32 v[154:155], v[54:55], v[154:155]
	v_exp_f32_e32 v58, v58
	v_exp_f32_e32 v59, v59
	v_pk_add_f32 v[154:155], v[40:41], v[154:155]
	v_exp_f32_e32 v44, v44
	v_exp_f32_e32 v45, v45
	v_pk_add_f32 v[154:155], v[56:57], v[154:155]
	v_exp_f32_e32 v60, v60
	v_exp_f32_e32 v61, v61
	v_pk_add_f32 v[154:155], v[42:43], v[154:155]
	v_exp_f32_e32 v46, v46
	v_exp_f32_e32 v47, v47
	v_cvt_pk_bf16_f32 v164, v50, v51
	ds_read_b64_tr_b16 v[50:51],v150 offset:0
	v_pk_add_f32 v[154:155], v[58:59], v[154:155]
	v_exp_f32_e32 v62, v62
	v_exp_f32_e32 v63, v63
	v_cvt_pk_bf16_f32 v165, v52, v53
	ds_read_b64_tr_b16 v[52:53],v150 offset:512
	v_pk_add_f32 v[154:155], v[44:45], v[154:155]
	v_exp_f32_e32 v48, v48
	v_exp_f32_e32 v49, v49
	v_cvt_pk_bf16_f32 v166, v54, v55
	ds_read_b64_tr_b16 v[54:55],v150 offset:1024
	v_pk_add_f32 v[154:155], v[60:61], v[154:155]
	v_exp_f32_e32 v64, v64
	v_exp_f32_e32 v65, v65
	v_cvt_pk_bf16_f32 v167, v56, v57
	ds_read_b64_tr_b16 v[56:57],v150 offset:1536
	v_pk_add_f32 v[154:155], v[46:47], v[154:155]
	v_cvt_pk_bf16_f32 v168, v58, v59
	ds_read_b64_tr_b16 v[58:59],v150 offset:2048
	v_pk_add_f32 v[154:155], v[62:63], v[154:155]
	v_cvt_pk_bf16_f32 v169, v60, v61
	ds_read_b64_tr_b16 v[60:61],v150 offset:2560
	v_pk_add_f32 v[154:155], v[48:49], v[154:155]
	v_cvt_pk_bf16_f32 v170, v62, v63
	ds_read_b64_tr_b16 v[62:63],v150 offset:3072
	v_pk_add_f32 v[154:155], v[64:65], v[154:155]
	v_cvt_pk_bf16_f32 v171, v64, v65
	ds_read_b64_tr_b16 v[64:65],v150 offset:3584
	s_waitcnt lgkmcnt(0)
	v_add_f32_e32 v154, v154, v155
	v_add_f32_e32 v154, v148, v154
	v_cvt_pk_bf16_f32 v156, v34, v35
	v_cvt_pk_bf16_f32 v157, v36, v37
	v_cvt_pk_bf16_f32 v158, v38, v39
	v_cvt_pk_bf16_f32 v159, v40, v41
	v_cvt_pk_bf16_f32 v160, v42, v43
	v_cvt_pk_bf16_f32 v161, v44, v45
	v_cvt_pk_bf16_f32 v162, v46, v47
	v_cvt_pk_bf16_f32 v163, v48, v49
	v_mfma_f32_32x32x16_bf16 v[2:17], v[156:159], v[50:53], v[2:17]
	ds_read_b64_tr_b16 v[172:173],v150 offset:4096
	ds_read_b64_tr_b16 v[174:175],v150 offset:4608
	ds_read_b64_tr_b16 v[176:177],v150 offset:5120
	ds_read_b64_tr_b16 v[178:179],v150 offset:5632
	ds_read_b64_tr_b16 v[180:181],v150 offset:6144
	ds_read_b64_tr_b16 v[182:183],v150 offset:6656
	ds_read_b64_tr_b16 v[184:185],v150 offset:7168
	s_nop 0
	v_mfma_f32_32x32x16_bf16 v[2:17], v[160:163], v[54:57], v[2:17]
	ds_read_b64_tr_b16 v[186:187],v150 offset:7680
	s_waitcnt lgkmcnt(0)
	v_mfma_f32_32x32x16_bf16 v[2:17], v[164:167], v[58:61], v[2:17]
	v_mfma_f32_32x32x16_bf16 v[2:17], v[168:171], v[62:65], v[2:17]
	v_mfma_f32_32x32x16_bf16 v[18:33], v[156:159], v[172:175], v[18:33]
	s_mov_b64 s[66:67], 0
	v_mfma_f32_32x32x16_bf16 v[18:33], v[160:163], v[176:179], v[18:33]
	v_mfma_f32_32x32x16_bf16 v[18:33], v[164:167], v[180:183], v[18:33]
	v_mfma_f32_32x32x16_bf16 v[18:33], v[168:171], v[184:187], v[18:33]

.LBB0_808:
	s_cmp_lg_u32 s48, 1
	v_fma_f32 v150, v151, s50, -v146
	s_cselect_b64 s[66:67], -1, 0
	v_cmp_nlt_f32_e64 s[68:69], v150, -v131
	v_fma_f32 v196, v151, s50, -v197
	v_cmp_lt_f32_e64 s[100:101], v196, -v131
	s_nop 3
	s_or_b64 s[98:99], s[98:99], s[100:101]
	s_and_b64 s[70:71], s[66:67], s[68:69]
	s_mov_b64 s[68:69], -1
	s_and_saveexec_b64 s[66:67], s[70:71]
	s_cbranch_execz .LBB0_775
	s_waitcnt lgkmcnt(0)
	s_barrier
	s_waitcnt vmcnt(8)
	s_nop 1
	v_add_f32_dpp v150, v139, v139 row_shl:1 row_mask:0xf bank_mask:0xf bound_ctrl:1
	s_nop 1
	v_add_f32_dpp v150, v150, v150 row_shl:2 row_mask:0xf bank_mask:0xf bound_ctrl:1
	s_nop 1
	v_add_f32_dpp v150, v150, v150 row_shl:4 row_mask:0xf bank_mask:0xf bound_ctrl:1
	s_nop 1
	v_add_f32_dpp v150, v150, v150 row_shl:8 row_mask:0xf bank_mask:0xf bound_ctrl:1
	s_nop 0
	v_readlane_b32 s28, v150, 16
	v_readlane_b32 s80, v150, 32
	v_readlane_b32 s78, v150, 48
	s_and_saveexec_b64 s[68:69], s[6:7]
	s_xor_b64 s[68:69], exec, s[68:69]
	s_cbranch_execz .LBB0_815
	s_and_saveexec_b64 s[70:71], s[8:9]
	s_xor_b64 s[70:71], exec, s[70:71]
	v_mov_b32_e32 v152, s78
	v_cndmask_b32_e64 v152, 0, v152, s[10:11]
	s_andn2_saveexec_b64 s[70:71], s[70:71]
	v_mov_b32_e32 v152, s78
	v_add_f32_e32 v152, s80, v152
	s_or_b64 exec, exec, s[70:71]
.LBB0_815:
	s_andn2_saveexec_b64 s[68:69], s[68:69]
	v_mov_b32_e32 v152, s80
	v_add_f32_e32 v152, s28, v152
	v_add_f32_e32 v152, s78, v152
	s_or_b64 exec, exec, s[68:69]
	v_add_f32_e32 v151, s79, v151
	v_add_f32_e32 v150, v150, v152
	v_add_f32_e32 v152, v151, v150
	v_sub_f32_e32 v139, v152, v139
	v_mul_f32_e32 v139, 0x3fb8aa3b, v139
	s_max_i32 s28, s48, 6
	ds_write_b32 v0, v139 offset:32768
	s_waitcnt vmcnt(4)
	ds_write_b128 v149, v[78:81]
	ds_write_b128 v149, v[86:89] offset:8192
	s_add_i32 s28, s28, -6
	s_waitcnt lgkmcnt(0)
	s_lshl_b64 s[68:69], s[28:29], 11
	v_lshl_add_u64 v[78:79], v[110:111], 0, s[68:69]
	global_load_dword v139, v[78:79], off
	s_lshl_b64 s[68:69], s[28:29], 16
	v_lshl_add_u64 v[86:87], v[106:107], 0, s[68:69]
	global_load_dwordx4 v[78:81], v[86:87], off
	v_lshl_add_u64 v[152:153], v[108:109], 0, s[68:69]
	global_load_dwordx4 v[86:89], v[152:153], off
	v_readfirstlane_b32 s70, v150
	s_andn2_b64 vcc, exec, s[60:61]
	s_mov_b64 s[68:69], -1
	s_cbranch_vccnz .LBB0_819
	s_add_i32 s28, s75, 0xffffff40
	s_mov_b64 s[68:69], 0
